# attention row-max chain (doc 7.12): tree reduces the earlier MFMA's accumulator first, v_max(x,x) canonicalisations dropped, permlane wait states filled with the first-tile compare
# baseline (speedup 1.0000x reference)
; __device__ __forceinline__ void attn_unit(const bf16* __restrict__ QB, const bf16* __restrict__ KB, const bf16* __restrict__ VB, bf16* __restrict__ YATT, ...
;     ...
;             float mx = fmaxf(s0[0], s1[0]);
; #pragma unroll
;             for (int r = 1; r < 16; ++r) mx = fmaxf(mx, fmaxf(s0[r], s1[r]));
;             { auto rr = __builtin_amdgcn_permlane32_swap(__float_as_uint(mx), __float_as_uint(mx), false, false); mx = fmaxf(__uint_as_float(rr[0]), __uint_as_float(rr[1])); }
;             const bool need = (j == jsw) || (mx > THR);
;             if (__any(need)) {
;                 const float delta = need ? mx : 0.f;
;                 const float alpha = (j == jsw) ? 1.f : __builtin_amdgcn_exp2f(-delta);
;                 lrun *= alpha;
; #pragma unroll
;                 for (int r = 0; r < 16; ++r) { s0[r] -= delta; s1[r] -= delta; negc[r] -= delta; }
; #pragma unroll
;                 for (int e = 0; e < 4; ++e)
; #pragma unroll
;                     for (int r = 0; r < 16; ++r) acc[e][r] *= alpha;
.LBB0_577:
	s_or_b64 exec, exec, s[78:79]
	s_nop 8
	v_max3_f32 v2, v114, v115, v116
	v_max3_f32 v3, v117, v118, v119
	v_max3_f32 v4, v120, v121, v122
	v_max3_f32 v6, v123, v124, v125
	v_max3_f32 v2, v2, v126, v127
	v_max3_f32 v3, v3, v128, v129
	v_max3_f32 v4, v4, v98, v99
	v_max3_f32 v6, v6, v100, v101
	v_max3_f32 v2, v2, v102, v103
	v_max3_f32 v3, v3, v104, v105
	v_max3_f32 v4, v4, v106, v107
	v_max3_f32 v6, v6, v108, v109
	v_max3_f32 v2, v2, v110, v111
	v_max3_f32 v3, v3, v112, v113
	v_max3_f32 v2, v2, v3, v4
	v_max_f32_e32 v2, v2, v6
	v_mov_b32_e32 v3, v2
	v_cmp_eq_u32_e64 s[8:9], s81, v206
	s_mov_b32 s10, 0x42700000
	v_permlane32_swap_b32_e32 v2, v3
	v_max_f32_e32 v2, v2, v3
	v_cmp_lt_f32_e32 vcc, s10, v2
	s_or_b64 vcc, s[8:9], vcc
	s_cbranch_vccz .LBB0_579
	v_cndmask_b32_e32 v2, 0, v2, vcc
	v_exp_f32_e64 v3, -v2
	v_sub_f32_e32 v97, v97, v2
	v_sub_f32_e32 v96, v96, v2
	v_sub_f32_e32 v95, v95, v2
	v_cndmask_b32_e64 v4, v3, 1.0, s[8:9]
	v_pk_add_f32 v[114:115], v[114:115], v[2:3] op_sel_hi:[1,0] neg_lo:[0,1] neg_hi:[0,1]
	v_pk_add_f32 v[98:99], v[98:99], v[2:3] op_sel_hi:[1,0] neg_lo:[0,1] neg_hi:[0,1]
	v_pk_add_f32 v[116:117], v[116:117], v[2:3] op_sel_hi:[1,0] neg_lo:[0,1] neg_hi:[0,1]
	v_pk_add_f32 v[100:101], v[100:101], v[2:3] op_sel_hi:[1,0] neg_lo:[0,1] neg_hi:[0,1]
	v_pk_add_f32 v[118:119], v[118:119], v[2:3] op_sel_hi:[1,0] neg_lo:[0,1] neg_hi:[0,1]
	v_pk_add_f32 v[102:103], v[102:103], v[2:3] op_sel_hi:[1,0] neg_lo:[0,1] neg_hi:[0,1]
	v_pk_add_f32 v[120:121], v[120:121], v[2:3] op_sel_hi:[1,0] neg_lo:[0,1] neg_hi:[0,1]
	v_pk_add_f32 v[104:105], v[104:105], v[2:3] op_sel_hi:[1,0] neg_lo:[0,1] neg_hi:[0,1]
	v_pk_add_f32 v[122:123], v[122:123], v[2:3] op_sel_hi:[1,0] neg_lo:[0,1] neg_hi:[0,1]
	v_pk_add_f32 v[106:107], v[106:107], v[2:3] op_sel_hi:[1,0] neg_lo:[0,1] neg_hi:[0,1]
	v_pk_add_f32 v[124:125], v[124:125], v[2:3] op_sel_hi:[1,0] neg_lo:[0,1] neg_hi:[0,1]
	v_pk_add_f32 v[108:109], v[108:109], v[2:3] op_sel_hi:[1,0] neg_lo:[0,1] neg_hi:[0,1]
	v_pk_add_f32 v[126:127], v[126:127], v[2:3] op_sel_hi:[1,0] neg_lo:[0,1] neg_hi:[0,1]
	v_pk_add_f32 v[110:111], v[110:111], v[2:3] op_sel_hi:[1,0] neg_lo:[0,1] neg_hi:[0,1]
	v_pk_add_f32 v[128:129], v[128:129], v[2:3] op_sel_hi:[1,0] neg_lo:[0,1] neg_hi:[0,1]
	v_pk_add_f32 v[112:113], v[112:113], v[2:3] op_sel_hi:[1,0] neg_lo:[0,1] neg_hi:[0,1]
	v_sub_f32_e32 v94, v94, v2
	v_sub_f32_e32 v93, v93, v2
	v_sub_f32_e32 v92, v92, v2
	v_sub_f32_e32 v91, v91, v2
	v_sub_f32_e32 v90, v90, v2
	v_sub_f32_e32 v89, v89, v2
	v_sub_f32_e32 v88, v88, v2
	v_sub_f32_e32 v87, v87, v2
	v_sub_f32_e32 v86, v86, v2
	v_sub_f32_e32 v85, v85, v2
	v_sub_f32_e32 v84, v84, v2
	v_sub_f32_e32 v83, v83, v2
	v_sub_f32_e32 v82, v82, v2
	s_cmp_eq_u64 s[8:9], exec
	s_cbranch_scc1 .Lattn_a1
	v_pk_mul_f32 v[80:81], v[80:81], v[4:5] op_sel_hi:[1,0]
	v_pk_mul_f32 v[78:79], v[78:79], v[4:5] op_sel_hi:[1,0]
	v_pk_mul_f32 v[76:77], v[76:77], v[4:5] op_sel_hi:[1,0]
	v_pk_mul_f32 v[74:75], v[74:75], v[4:5] op_sel_hi:[1,0]
	v_pk_mul_f32 v[72:73], v[72:73], v[4:5] op_sel_hi:[1,0]
	v_pk_mul_f32 v[70:71], v[70:71], v[4:5] op_sel_hi:[1,0]
	v_pk_mul_f32 v[68:69], v[68:69], v[4:5] op_sel_hi:[1,0]
	v_pk_mul_f32 v[66:67], v[66:67], v[4:5] op_sel_hi:[1,0]
	v_pk_mul_f32 v[64:65], v[64:65], v[4:5] op_sel_hi:[1,0]
	v_pk_mul_f32 v[62:63], v[62:63], v[4:5] op_sel_hi:[1,0]
	v_pk_mul_f32 v[60:61], v[60:61], v[4:5] op_sel_hi:[1,0]
	v_pk_mul_f32 v[58:59], v[58:59], v[4:5] op_sel_hi:[1,0]
	v_pk_mul_f32 v[56:57], v[56:57], v[4:5] op_sel_hi:[1,0]
	v_pk_mul_f32 v[54:55], v[54:55], v[4:5] op_sel_hi:[1,0]
	v_pk_mul_f32 v[52:53], v[52:53], v[4:5] op_sel_hi:[1,0]
	v_pk_mul_f32 v[50:51], v[50:51], v[4:5] op_sel_hi:[1,0]
	v_pk_mul_f32 v[48:49], v[48:49], v[4:5] op_sel_hi:[1,0]
	v_pk_mul_f32 v[46:47], v[46:47], v[4:5] op_sel_hi:[1,0]
	v_pk_mul_f32 v[44:45], v[44:45], v[4:5] op_sel_hi:[1,0]
	v_pk_mul_f32 v[42:43], v[42:43], v[4:5] op_sel_hi:[1,0]
	v_pk_mul_f32 v[40:41], v[40:41], v[4:5] op_sel_hi:[1,0]
	v_pk_mul_f32 v[38:39], v[38:39], v[4:5] op_sel_hi:[1,0]
	v_pk_mul_f32 v[36:37], v[36:37], v[4:5] op_sel_hi:[1,0]
	v_pk_mul_f32 v[34:35], v[34:35], v[4:5] op_sel_hi:[1,0]
	v_pk_mul_f32 v[32:33], v[32:33], v[4:5] op_sel_hi:[1,0]
	v_pk_mul_f32 v[30:31], v[30:31], v[4:5] op_sel_hi:[1,0]
	v_pk_mul_f32 v[28:29], v[28:29], v[4:5] op_sel_hi:[1,0]
	v_pk_mul_f32 v[26:27], v[26:27], v[4:5] op_sel_hi:[1,0]
	v_pk_mul_f32 v[24:25], v[24:25], v[4:5] op_sel_hi:[1,0]
	v_pk_mul_f32 v[22:23], v[22:23], v[4:5] op_sel_hi:[1,0]
	v_pk_mul_f32 v[20:21], v[20:21], v[4:5] op_sel_hi:[1,0]
	v_pk_mul_f32 v[18:19], v[18:19], v[4:5] op_sel_hi:[1,0]
	v_mul_f32_e32 v207, v207, v4
